# P6 loop: K/V tile loads via SGPR tile base + 32-bit lane offset (no 64-bit VALU pointer math), uniform mask inversion on SALU, row-sum update folded into one fma
# speedup vs baseline: 1.0239x; 1.0067x over previous
; __device__ __forceinline__ int v_st(int k, int c) { const int kk = (k & ~0xC) | ((k & 4) << 1) | ((k & 8) >> 1); return ((kk >> 3) * 4 + (c >> 5)) * 512 + ((kk & 7) * 32 + (c & 31)) * 2; }
; __device__ __forceinline__ int v_rd_base(int lane) { return ((lane & 3) << 3) | (((lane >> 2) & 3) << 6) | (((lane >> 4) & 1) << 5) | (((lane >> 5) & 1) << 8); }
; #define lane lane_id()
; template <int MODE>
; __device__ __forceinline__ void attn_block(const BlockRef& cur, const BlockRef& nxt, char* lds, Seam& S, int par, const int wid) {
;     constexpr bool SK = MODE == 2;
;     const int W = mode_w<MODE>();
;     const int lane = lane_id(), tid = wid * 64 + lane, r32 = lane & 31, hi = lane >> 5;
;     const int j_lo = swa_jlo(cur.P0, W);
;     constexpr int WROWS = MODE == 2 ? 8 : QBLK, BROWS = MODE == 2 ? 64 : QB;
;     const int j_hi = (cur.P0 + BROWS - 1) / KVBLK + 1;
;     const int NT = j_hi - j_lo;
;     const int kbn = swa_jlo(nxt.P0, W) * KVBLK;
;     const int qlo = cur.P0 + wid * WROWS, qm = qlo + (MODE == 2 ? (r32 & 7) : r32) - 4 * hi;
;     char* V_lds = lds; char* K_lds = lds + 2 * SHM_V;
;     float* ws = (float*)(lds + 2 * SHM_V + 2 * SHM_K) + wid * 64; float* li_l = ws, * al_l = ws + 32;
;     const float* tb = cur.tb + (MODE == 2 ? (r32 >> 3) * TBXN : 0);
;     const unsigned* selrow = (const unsigned*)(lds + LDS_SEL + par * 2048) + (wid * 8 + (r32 & 7)) * 8;
;     unsigned selw = 0u;
;     float m_reg = -1e30f, l_reg = 0; f32x16 o[4] = {};
;     const int sr = tid >> 4, sc = (tid & 15) * 8, vst0 = v_st(sr, sc), vst1 = v_st(32 + sr, sc), kws = KSWZ(sr, sc * 2);
;     const unsigned loff = (unsigned)(sr * D + sc) * 2u;
;     const int vb0 = (int)(uintptr_t)V_lds + v_rd_base(lane);
;     const bf16_t* Kh = cur.K; const bf16_t* Vh = cur.V;
.LBB0_1327:
	v_lshlrev_b32_e32 v2, 4, v219
	s_add_i32 s46, s0, 7
	s_add_i32 s1, s8, 63
	v_and_b32_e32 v2, 0xc0, v2
	v_lshlrev_b32_e32 v3, 1, v219
	v_and_or_b32 v2, v19, 24, v2
	v_and_b32_e32 v3, 32, v3
	v_and_b32_e32 v4, 0x100, v19
	s_cmp_lg_u32 0, -1
	v_or3_b32 v2, v2, v3, v4
	s_cselect_b32 s2, 0, 0
	v_add_u32_e32 v226, s2, v2
	s_cmpk_lt_u32 s8, 0x41
	v_cmp_gt_u32_e64 s[2:3], 32, v219
	v_lshl_add_u32 v225, v220, 2, s26
	v_lshl_add_u32 v224, v221, 2, s26
	s_waitcnt lgkmcnt(0)
	s_barrier
	s_cbranch_scc1 .LBB0_1434
	v_lshlrev_b32_e32 v2, 4, v220
	v_and_b32_e32 v2, 0x70, v2
	v_or_b32_e32 v3, 32, v212
	v_xad_u32 v19, v3, v2, 0
	v_or_b32_e32 v3, 64, v212
	v_xad_u32 v20, v3, v2, 0
	v_or_b32_e32 v3, 0x60, v212
	v_xad_u32 v17, v212, v2, 0
	v_xad_u32 v21, v3, v2, 0
	v_add_u32_e32 v2, s8, v231
	v_lshl_add_u32 v0, v2, 2, v0
	v_sub_u32_e32 v0, v0, v212
	s_add_i32 s4, s36, s8
	v_add_u32_e32 v237, s38, v0
	v_add_u32_e32 v0, s4, v231
	v_sub_u32_e32 v238, v0, v221
	v_add_lshl_u32 v0, s92, v219, 4
	s_movk_i32 s4, 0x3f00
	v_lshlrev_b32_e32 v16, 8, v220
	v_and_or_b32 v0, v0, s4, v18
	v_mov_b32_e32 v14, v1
	v_mov_b32_e32 v15, v1
	v_mov_b32_e32 v248, v0
	v_add_u32_e32 v249, 0x2000, v0
	s_mov_b64 s[98:99], s[70:71]
	s_add_u32 s100, s70, 0x1000000
	s_addc_u32 s101, s71, 0
	v_mov_b32_e32 v0, v1
	v_mov_b32_e32 v2, v1
	v_mov_b32_e32 v3, v1
	v_mov_b32_e32 v4, v1
	v_mov_b32_e32 v5, v1
	v_mov_b32_e32 v6, v1
	v_mov_b32_e32 v7, v1
	v_mov_b32_e32 v8, v1
	v_mov_b32_e32 v9, v1
	v_mov_b32_e32 v10, v1
	v_mov_b32_e32 v11, v1
	v_mov_b32_e32 v12, v1
	v_mov_b32_e32 v13, v1
	v_add_u32_e32 v239, v17, v16
	v_add_u32_e32 v240, v19, v16
	v_add_u32_e32 v241, v20, v16
	v_add_u32_e32 v242, v21, v16
	v_mov_b64_e32 v[78:79], v[14:15]
	v_mov_b64_e32 v[62:63], v[14:15]
	v_mov_b64_e32 v[46:47], v[14:15]
	v_mov_b64_e32 v[30:31], v[14:15]
	v_mov_b64_e32 v[126:127], v[14:15]
	s_lshr_b32 s47, s1, 6
	s_add_i32 s88, s0, 0xc0000001
	v_mov_b32_e32 v227, 0
	s_movk_i32 s95, 0x130
	s_mov_b32 s96, 3
	v_mov_b64_e32 v[76:77], v[12:13]
	v_mov_b64_e32 v[74:75], v[10:11]
	v_mov_b64_e32 v[72:73], v[8:9]
	v_mov_b64_e32 v[70:71], v[6:7]
	v_mov_b64_e32 v[68:69], v[4:5]
	v_mov_b64_e32 v[66:67], v[2:3]
	v_mov_b64_e32 v[64:65], v[0:1]
	v_mov_b64_e32 v[60:61], v[12:13]
	v_mov_b64_e32 v[58:59], v[10:11]
	v_mov_b64_e32 v[56:57], v[8:9]
	v_mov_b64_e32 v[54:55], v[6:7]
	v_mov_b64_e32 v[52:53], v[4:5]
	v_mov_b64_e32 v[50:51], v[2:3]
	v_mov_b64_e32 v[48:49], v[0:1]
	v_mov_b64_e32 v[44:45], v[12:13]
	v_mov_b64_e32 v[42:43], v[10:11]
	v_mov_b64_e32 v[40:41], v[8:9]
	v_mov_b64_e32 v[38:39], v[6:7]
	v_mov_b64_e32 v[36:37], v[4:5]
	v_mov_b64_e32 v[34:35], v[2:3]
	v_mov_b64_e32 v[32:33], v[0:1]
	v_mov_b64_e32 v[28:29], v[12:13]
	v_mov_b64_e32 v[26:27], v[10:11]
	v_mov_b64_e32 v[24:25], v[8:9]
	v_mov_b64_e32 v[22:23], v[6:7]
	v_mov_b64_e32 v[20:21], v[4:5]
	v_mov_b64_e32 v[18:19], v[2:3]
	v_mov_b64_e32 v[16:17], v[0:1]
	v_mov_b64_e32 v[124:125], v[12:13]
	v_mov_b64_e32 v[122:123], v[10:11]
	v_mov_b64_e32 v[120:121], v[8:9]
	v_mov_b64_e32 v[118:119], v[6:7]
	v_mov_b64_e32 v[116:117], v[4:5]
	v_mov_b64_e32 v[114:115], v[2:3]
	v_mov_b64_e32 v[112:113], v[0:1]
	s_add_i32 s5, s96, -2
	s_and_b32 s4, s5, 31
	s_cmp_lg_u32 s4, 0
	s_cbranch_scc1 .LBB0_1330

; __device__ __forceinline__ void finishSM(f32x16& p0, f32x16& p1, float alpha, float& l_reg, bf16x8& pa0, bf16x8& pa1, bf16x8& pa2, bf16x8& pa3) {
; #pragma unroll
;     for (int r = 0; r < 16; ++r) p1[r] = __builtin_amdgcn_exp2f(p1[r]);
;     float ps = 0;
; #pragma unroll
;     for (int r = 0; r < 16; ++r) ps += p0[r];
; #pragma unroll
;     for (int r = 0; r < 16; ++r) ps += p1[r];
;     { auto rr = __builtin_amdgcn_permlane32_swap(__float_as_uint(ps), __float_as_uint(ps), false, false);
;       ps = __uint_as_float(rr[0]) + __uint_as_float(rr[1]); }
;     l_reg = l_reg * alpha + ps;
;     PK4(p0, 0, pa0); PK4(p0, 8, pa1); PK4(p1, 0, pa2); PK4(p1, 8, pa3);
; }
; template <int KB, bool SK>
; __device__ __forceinline__ void qkt(f32x16& p0, f32x16& p1, const char* K_lds, int r32, int hi, const bf16x8* qr, bool act) {
;     if (SK && !act) return;
;     p0 = f32x16{}; p1 = f32x16{};
;     const char* kb[4];
; #pragma unroll
;     for (int dd = 0; dd < 4; ++dd) kb[dd] = K_lds + KB * SHM_K + KSWZ(r32, (dd * 16 + hi * 8) * 2);
; #pragma unroll
;     for (int d0 = 0; d0 < 8; ++d0) { const char* a = kb[d0 & 3] + (d0 >> 2) * 128;
;         bf16x8 b0 = *reinterpret_cast<const bf16x8*>(a);
;         bf16x8 b1 = *reinterpret_cast<const bf16x8*>(a + 32 * 256);
;         p0 = __builtin_amdgcn_mfma_f32_32x32x16_bf16(b0, qr[d0], p0, 0, 0, 0);
;         p1 = __builtin_amdgcn_mfma_f32_32x32x16_bf16(b1, qr[d0], p1, 0, 0, 0); }
; }
.LBB0_1332:
	s_waitcnt vmcnt(3)
	s_andn2_b64 s[4:5], exec, s[82:83]
	s_andn2_b64 vcc, exec, s[82:83]
	s_cbranch_vccnz .LBB0_1334
	ds_read_b128 v[2:5], v239 offset:49152
	ds_read_b128 v[6:9], v239 offset:57344
	ds_read_b128 v[10:13], v240 offset:49152
	ds_read_b128 v[144:147], v240 offset:57344
	ds_read_b128 v[148:151], v241 offset:49152
	ds_read_b128 v[152:155], v241 offset:57344
	s_waitcnt lgkmcnt(5)
	v_mfma_f32_32x32x16_bf16 v[112:127], v[2:5], v[188:191], 0
	ds_read_b128 v[2:5], v242 offset:49152
	s_waitcnt lgkmcnt(5)
	v_mfma_f32_32x32x16_bf16 v[80:95], v[6:9], v[188:191], 0
	ds_read_b128 v[6:9], v242 offset:57344
	s_waitcnt lgkmcnt(5)
	v_mfma_f32_32x32x16_bf16 v[112:127], v[10:13], v[184:187], v[112:127]
	ds_read_b128 v[10:13], v239 offset:49280
	s_waitcnt lgkmcnt(5)
	v_mfma_f32_32x32x16_bf16 v[80:95], v[144:147], v[184:187], v[80:95]
	ds_read_b128 v[144:147], v239 offset:57472
	s_waitcnt lgkmcnt(5)
	v_mfma_f32_32x32x16_bf16 v[112:127], v[148:151], v[180:183], v[112:127]
	ds_read_b128 v[148:151], v240 offset:49280
	s_waitcnt lgkmcnt(5)
	v_mfma_f32_32x32x16_bf16 v[80:95], v[152:155], v[180:183], v[80:95]
	ds_read_b128 v[152:155], v240 offset:57472
	s_waitcnt lgkmcnt(5)
	v_mfma_f32_32x32x16_bf16 v[112:127], v[2:5], v[176:179], v[112:127]
	ds_read_b128 v[2:5], v241 offset:49280
	s_waitcnt lgkmcnt(5)
	v_mfma_f32_32x32x16_bf16 v[80:95], v[6:9], v[176:179], v[80:95]
	ds_read_b128 v[6:9], v241 offset:57472
	s_waitcnt lgkmcnt(5)
	v_mfma_f32_32x32x16_bf16 v[112:127], v[10:13], v[172:175], v[112:127]
	ds_read_b128 v[10:13], v242 offset:49280
	s_waitcnt lgkmcnt(5)
	v_mfma_f32_32x32x16_bf16 v[80:95], v[144:147], v[172:175], v[80:95]
	ds_read_b128 v[144:147], v242 offset:57472
	s_waitcnt lgkmcnt(5)
	v_mfma_f32_32x32x16_bf16 v[112:127], v[148:151], v[168:171], v[112:127]
	s_waitcnt lgkmcnt(4)
	v_mfma_f32_32x32x16_bf16 v[80:95], v[152:155], v[168:171], v[80:95]
	s_waitcnt lgkmcnt(3)
	v_mfma_f32_32x32x16_bf16 v[112:127], v[2:5], v[164:167], v[112:127]
	s_waitcnt lgkmcnt(2)
	v_mfma_f32_32x32x16_bf16 v[80:95], v[6:9], v[164:167], v[80:95]
	s_waitcnt lgkmcnt(1)
	v_mfma_f32_32x32x16_bf16 v[112:127], v[10:13], v[160:163], v[112:127]
	s_waitcnt lgkmcnt(0)
	v_mfma_f32_32x32x16_bf16 v[80:95], v[144:147], v[160:163], v[80:95]
.LBB0_1334:
	s_andn2_b64 s[6:7], exec, s[84:85]
	s_andn2_b64 vcc, exec, s[84:85]
	s_cbranch_vccnz .LBB0_1336
	v_add_f32_e32 v2, v128, v129
	v_add_f32_e32 v2, v130, v2
	v_add_f32_e32 v2, v131, v2
	v_add_f32_e32 v2, v132, v2
	v_add_f32_e32 v2, v133, v2
	v_add_f32_e32 v2, v134, v2
	v_add_f32_e32 v2, v135, v2
	v_add_f32_e32 v2, v136, v2
	v_add_f32_e32 v2, v137, v2
	v_add_f32_e32 v2, v138, v2
	v_add_f32_e32 v2, v139, v2
	v_exp_f32_e32 v96, v96
	v_add_f32_e32 v2, v140, v2
	v_exp_f32_e32 v97, v97
	v_add_f32_e32 v2, v141, v2
	v_exp_f32_e32 v98, v98
	v_add_f32_e32 v2, v142, v2
	v_exp_f32_e32 v99, v99
	v_add_f32_e32 v2, v143, v2
	v_exp_f32_e32 v100, v100
	v_add_f32_e32 v2, v96, v2
	v_exp_f32_e32 v101, v101
	v_add_f32_e32 v2, v97, v2
	v_exp_f32_e32 v102, v102
	v_add_f32_e32 v2, v98, v2
	v_exp_f32_e32 v103, v103
	v_add_f32_e32 v2, v99, v2
	v_exp_f32_e32 v104, v104
	v_add_f32_e32 v2, v100, v2
	v_exp_f32_e32 v105, v105
	v_add_f32_e32 v2, v101, v2
	v_exp_f32_e32 v106, v106
	v_add_f32_e32 v2, v102, v2
	v_exp_f32_e32 v107, v107
	v_add_f32_e32 v2, v103, v2
	v_exp_f32_e32 v108, v108
	v_add_f32_e32 v2, v104, v2
	v_exp_f32_e32 v109, v109
	v_add_f32_e32 v2, v105, v2
	v_exp_f32_e32 v110, v110
	v_add_f32_e32 v2, v106, v2
	v_exp_f32_e32 v111, v111
	v_add_f32_e32 v2, v107, v2
	v_add_f32_e32 v2, v108, v2
	v_add_f32_e32 v2, v109, v2
	v_add_f32_e32 v2, v110, v2
	v_add_f32_e32 v2, v111, v2
	v_mov_b32_e32 v3, v2
	s_nop 1
	v_permlane32_swap_b32_e32 v2, v3
	v_add_f32_e32 v2, v2, v3
	v_fma_f32 v227, v243, v227, v2
	v_cvt_pk_bf16_f32 v192, v128, v129
	v_cvt_pk_bf16_f32 v193, v130, v131
	v_cvt_pk_bf16_f32 v194, v132, v133
	v_cvt_pk_bf16_f32 v195, v134, v135
	v_cvt_pk_bf16_f32 v196, v136, v137
	v_cvt_pk_bf16_f32 v197, v138, v139
	v_cvt_pk_bf16_f32 v198, v140, v141
	v_cvt_pk_bf16_f32 v199, v142, v143
	v_cvt_pk_bf16_f32 v200, v96, v97
	v_cvt_pk_bf16_f32 v201, v98, v99
	v_cvt_pk_bf16_f32 v202, v100, v101
	v_cvt_pk_bf16_f32 v203, v102, v103
	v_cvt_pk_bf16_f32 v204, v104, v105
	v_cvt_pk_bf16_f32 v205, v106, v107
	v_cvt_pk_bf16_f32 v206, v108, v109
	v_cvt_pk_bf16_f32 v207, v110, v111
	s_nop 0
	v_permlane32_swap_b32_e32 v192, v194
	v_permlane32_swap_b32_e32 v193, v195
	v_permlane32_swap_b32_e32 v196, v198
	v_permlane32_swap_b32_e32 v197, v199
	v_permlane32_swap_b32_e32 v200, v202
	v_permlane32_swap_b32_e32 v201, v203
	v_permlane32_swap_b32_e32 v204, v206
	v_permlane32_swap_b32_e32 v205, v207
; template <int VB, bool SK>
; __device__ __forceinline__ void pv_tile(f32x16* o, int vb0, bf16x8 pa0, bf16x8 pa1, bf16x8 pa2, bf16x8 pa3, bool act) {
;     if (SK && !act) return;
;     ...
;     PV_D0(0); PV_D0(1); PV_D0(2); PV_D0(3);
;     ...
; }
.LBB0_1336:
	s_mov_b32 s20, 0x1000000
	global_load_dwordx4 v[10:13], v248, s[98:99]
	global_load_dwordx4 v[208:211], v249, s[98:99]
	global_load_dwordx4 v[2:5], v248, s[100:101]
	global_load_dwordx4 v[6:9], v249, s[100:101]
	s_add_u32 s98, s98, 0x4000
	s_addc_u32 s99, s99, 0
	s_add_u32 s100, s100, 0x4000
	s_addc_u32 s101, s101, 0
	s_and_b64 vcc, exec, s[6:7]
	s_cbranch_vccnz .LBB0_1338
	s_waitcnt vmcnt(7)
	ds_read_b64_tr_b16 v[144:145], v226 offset:0
	ds_read_b64_tr_b16 v[146:147], v226 offset:0x800
	s_waitcnt vmcnt(6)
	ds_read_b64_tr_b16 v[148:149], v226 offset:0x1000
	ds_read_b64_tr_b16 v[150:151], v226 offset:0x1800
	s_waitcnt vmcnt(5)
	ds_read_b64_tr_b16 v[152:153], v226 offset:0x2000
	ds_read_b64_tr_b16 v[154:155], v226 offset:0x2800
	s_waitcnt vmcnt(4)
	ds_read_b64_tr_b16 v[156:157], v226 offset:0x3000
	ds_read_b64_tr_b16 v[158:159], v226 offset:0x3800
	s_waitcnt lgkmcnt(0)
	v_mfma_f32_32x32x16_bf16 v[64:79], v[192:195], v[144:147], v[64:79]
	ds_read_b64_tr_b16 v[144:145], v226 offset:0x200
	ds_read_b64_tr_b16 v[146:147], v226 offset:0xa00
	v_mfma_f32_32x32x16_bf16 v[64:79], v[196:199], v[148:151], v[64:79]
	ds_read_b64_tr_b16 v[148:149], v226 offset:0x1200
	ds_read_b64_tr_b16 v[150:151], v226 offset:0x1a00
	v_mfma_f32_32x32x16_bf16 v[64:79], v[200:203], v[152:155], v[64:79]
	ds_read_b64_tr_b16 v[152:153], v226 offset:0x2200
	ds_read_b64_tr_b16 v[154:155], v226 offset:0x2a00
	v_mfma_f32_32x32x16_bf16 v[64:79], v[204:207], v[156:159], v[64:79]
	ds_read_b64_tr_b16 v[156:157], v226 offset:0x3200
	ds_read_b64_tr_b16 v[158:159], v226 offset:0x3a00
	s_waitcnt lgkmcnt(0)
	v_mfma_f32_32x32x16_bf16 v[48:63], v[192:195], v[144:147], v[48:63]
	ds_read_b64_tr_b16 v[144:145], v226 offset:0x400
	ds_read_b64_tr_b16 v[146:147], v226 offset:0xc00
	v_mfma_f32_32x32x16_bf16 v[48:63], v[196:199], v[148:151], v[48:63]
	ds_read_b64_tr_b16 v[148:149], v226 offset:0x1400
	ds_read_b64_tr_b16 v[150:151], v226 offset:0x1c00
	v_mfma_f32_32x32x16_bf16 v[48:63], v[200:203], v[152:155], v[48:63]
	ds_read_b64_tr_b16 v[152:153], v226 offset:0x2400
	ds_read_b64_tr_b16 v[154:155], v226 offset:0x2c00
	v_mfma_f32_32x32x16_bf16 v[48:63], v[204:207], v[156:159], v[48:63]
	ds_read_b64_tr_b16 v[156:157], v226 offset:0x3400
	ds_read_b64_tr_b16 v[158:159], v226 offset:0x3c00
	s_waitcnt lgkmcnt(0)
	v_mfma_f32_32x32x16_bf16 v[32:47], v[192:195], v[144:147], v[32:47]
	ds_read_b64_tr_b16 v[144:145], v226 offset:0x600
	ds_read_b64_tr_b16 v[146:147], v226 offset:0xe00
	v_mfma_f32_32x32x16_bf16 v[32:47], v[196:199], v[148:151], v[32:47]
	ds_read_b64_tr_b16 v[148:149], v226 offset:0x1600
	ds_read_b64_tr_b16 v[150:151], v226 offset:0x1e00
	v_mfma_f32_32x32x16_bf16 v[32:47], v[200:203], v[152:155], v[32:47]
	ds_read_b64_tr_b16 v[152:153], v226 offset:0x2600
	ds_read_b64_tr_b16 v[154:155], v226 offset:0x2e00
	v_mfma_f32_32x32x16_bf16 v[32:47], v[204:207], v[156:159], v[32:47]
	ds_read_b64_tr_b16 v[156:157], v226 offset:0x3600
	ds_read_b64_tr_b16 v[158:159], v226 offset:0x3e00
	s_waitcnt lgkmcnt(0)
	v_mfma_f32_32x32x16_bf16 v[16:31], v[192:195], v[144:147], v[16:31]
	v_mfma_f32_32x32x16_bf16 v[16:31], v[196:199], v[148:151], v[16:31]
	v_mfma_f32_32x32x16_bf16 v[16:31], v[200:203], v[152:155], v[16:31]
	v_mfma_f32_32x32x16_bf16 v[16:31], v[204:207], v[156:159], v[16:31]

; __device__ __forceinline__ void finishSM(f32x16& p0, f32x16& p1, float alpha, float& l_reg, bf16x8& pa0, bf16x8& pa1, bf16x8& pa2, bf16x8& pa3) {
; #pragma unroll
;     for (int r = 0; r < 16; ++r) p1[r] = __builtin_amdgcn_exp2f(p1[r]);
;     float ps = 0;
; #pragma unroll
;     for (int r = 0; r < 16; ++r) ps += p0[r];
; #pragma unroll
;     for (int r = 0; r < 16; ++r) ps += p1[r];
;     { auto rr = __builtin_amdgcn_permlane32_swap(__float_as_uint(ps), __float_as_uint(ps), false, false);
;       ps = __uint_as_float(rr[0]) + __uint_as_float(rr[1]); }
;     l_reg = l_reg * alpha + ps;
;     PK4(p0, 0, pa0); PK4(p0, 8, pa1); PK4(p1, 0, pa2); PK4(p1, 8, pa3);
; }
; template <int KB, bool SK>
; __device__ __forceinline__ void qkt(f32x16& p0, f32x16& p1, const char* K_lds, int r32, int hi, const bf16x8* qr, bool act) {
;     ...
;     p0 = f32x16{}; p1 = f32x16{};
;     const char* kb[4];
; #pragma unroll
;     for (int dd = 0; dd < 4; ++dd) kb[dd] = K_lds + KB * SHM_K + KSWZ(r32, (dd * 16 + hi * 8) * 2);
; #pragma unroll
;     for (int d0 = 0; d0 < 8; ++d0) { const char* a = kb[d0 & 3] + (d0 >> 2) * 128;
;         bf16x8 b0 = *reinterpret_cast<const bf16x8*>(a);
;         bf16x8 b1 = *reinterpret_cast<const bf16x8*>(a + 32 * 256);
;         p0 = __builtin_amdgcn_mfma_f32_32x32x16_bf16(b0, qr[d0], p0, 0, 0, 0);
;         p1 = __builtin_amdgcn_mfma_f32_32x32x16_bf16(b1, qr[d0], p1, 0, 0, 0); }
.LBB0_1382:
	s_andn2_b64 s[6:7], exec, s[84:85]
	s_andn2_b64 vcc, exec, s[84:85]
	s_cbranch_vccnz .LBB0_1384
	ds_read_b128 v[144:147], v239 offset:32768
	ds_read_b128 v[148:151], v239 offset:40960
	ds_read_b128 v[152:155], v240 offset:32768
	ds_read_b128 v[156:159], v240 offset:40960
	ds_read_b128 v[244:247], v241 offset:32768
	ds_read_b128 v[252:255], v241 offset:40960
	s_waitcnt lgkmcnt(5)
	v_mfma_f32_32x32x16_bf16 v[128:143], v[144:147], v[188:191], 0
	ds_read_b128 v[144:147], v242 offset:32768
	s_waitcnt lgkmcnt(5)
	v_mfma_f32_32x32x16_bf16 v[96:111], v[148:151], v[188:191], 0
	ds_read_b128 v[148:151], v242 offset:40960
	s_waitcnt lgkmcnt(5)
	v_mfma_f32_32x32x16_bf16 v[128:143], v[152:155], v[184:187], v[128:143]
	ds_read_b128 v[152:155], v239 offset:32896
	s_waitcnt lgkmcnt(5)
	v_mfma_f32_32x32x16_bf16 v[96:111], v[156:159], v[184:187], v[96:111]
	ds_read_b128 v[156:159], v239 offset:41088
	s_waitcnt lgkmcnt(5)
	v_mfma_f32_32x32x16_bf16 v[128:143], v[244:247], v[180:183], v[128:143]
	ds_read_b128 v[244:247], v240 offset:32896
	s_waitcnt lgkmcnt(5)
	v_mfma_f32_32x32x16_bf16 v[96:111], v[252:255], v[180:183], v[96:111]
	ds_read_b128 v[252:255], v240 offset:41088
	s_waitcnt lgkmcnt(5)
	v_mfma_f32_32x32x16_bf16 v[128:143], v[144:147], v[176:179], v[128:143]
	ds_read_b128 v[144:147], v241 offset:32896
	s_waitcnt lgkmcnt(5)
	v_mfma_f32_32x32x16_bf16 v[96:111], v[148:151], v[176:179], v[96:111]
	ds_read_b128 v[148:151], v241 offset:41088
	s_waitcnt lgkmcnt(5)
	v_mfma_f32_32x32x16_bf16 v[128:143], v[152:155], v[172:175], v[128:143]
	ds_read_b128 v[152:155], v242 offset:32896
	s_waitcnt lgkmcnt(5)
	v_mfma_f32_32x32x16_bf16 v[96:111], v[156:159], v[172:175], v[96:111]
	ds_read_b128 v[156:159], v242 offset:41088
	s_waitcnt lgkmcnt(5)
	v_mfma_f32_32x32x16_bf16 v[128:143], v[244:247], v[168:171], v[128:143]
	s_waitcnt lgkmcnt(4)
	v_mfma_f32_32x32x16_bf16 v[96:111], v[252:255], v[168:171], v[96:111]
	s_waitcnt lgkmcnt(3)
	v_mfma_f32_32x32x16_bf16 v[128:143], v[144:147], v[164:167], v[128:143]
	s_waitcnt lgkmcnt(2)
	v_mfma_f32_32x32x16_bf16 v[96:111], v[148:151], v[164:167], v[96:111]
	s_waitcnt lgkmcnt(1)
	v_mfma_f32_32x32x16_bf16 v[128:143], v[152:155], v[160:163], v[128:143]
	s_waitcnt lgkmcnt(0)
	v_mfma_f32_32x32x16_bf16 v[96:111], v[156:159], v[160:163], v[96:111]
.LBB0_1384:
	s_and_b64 vcc, exec, s[4:5]
	s_cbranch_vccnz .LBB0_1386
	v_add_f32_e32 v15, v112, v113
	v_add_f32_e32 v15, v114, v15
	v_add_f32_e32 v15, v115, v15
	v_add_f32_e32 v15, v116, v15
	v_add_f32_e32 v15, v117, v15
	v_add_f32_e32 v15, v118, v15
	v_add_f32_e32 v15, v119, v15
	v_add_f32_e32 v15, v120, v15
	v_add_f32_e32 v15, v121, v15
	v_add_f32_e32 v15, v122, v15
	v_add_f32_e32 v15, v123, v15
	v_exp_f32_e32 v80, v80
	v_add_f32_e32 v15, v124, v15
	v_exp_f32_e32 v81, v81
	v_add_f32_e32 v15, v125, v15
	v_exp_f32_e32 v82, v82
	v_add_f32_e32 v15, v126, v15
	v_exp_f32_e32 v83, v83
	v_add_f32_e32 v15, v127, v15
	v_exp_f32_e32 v84, v84
	v_add_f32_e32 v15, v80, v15
	v_exp_f32_e32 v85, v85
	v_add_f32_e32 v15, v81, v15
	v_exp_f32_e32 v86, v86
	v_add_f32_e32 v15, v82, v15
	v_exp_f32_e32 v87, v87
	v_add_f32_e32 v15, v83, v15
	v_exp_f32_e32 v88, v88
	v_add_f32_e32 v15, v84, v15
	v_exp_f32_e32 v89, v89
	v_add_f32_e32 v15, v85, v15
	v_exp_f32_e32 v90, v90
	v_add_f32_e32 v15, v86, v15
	v_exp_f32_e32 v91, v91
	v_add_f32_e32 v15, v87, v15
	v_exp_f32_e32 v92, v92
	v_add_f32_e32 v15, v88, v15
	v_exp_f32_e32 v93, v93
	v_add_f32_e32 v15, v89, v15
	v_exp_f32_e32 v94, v94
	v_add_f32_e32 v15, v90, v15
	v_exp_f32_e32 v95, v95
	v_add_f32_e32 v15, v91, v15
	v_add_f32_e32 v15, v92, v15
	v_add_f32_e32 v15, v93, v15
	v_add_f32_e32 v15, v94, v15
	v_add_f32_e32 v15, v95, v15
	v_mov_b32_e32 v144, v15
	s_nop 1
	v_permlane32_swap_b32_e32 v15, v144
	v_add_f32_e32 v15, v15, v144
	v_fma_f32 v227, v227, v14, v15
	v_cvt_pk_bf16_f32 v192, v112, v113
	v_cvt_pk_bf16_f32 v193, v114, v115
	v_cvt_pk_bf16_f32 v194, v116, v117
	v_cvt_pk_bf16_f32 v195, v118, v119
	v_cvt_pk_bf16_f32 v196, v120, v121
	v_cvt_pk_bf16_f32 v197, v122, v123
	v_cvt_pk_bf16_f32 v198, v124, v125
	v_cvt_pk_bf16_f32 v199, v126, v127
	v_cvt_pk_bf16_f32 v200, v80, v81
	v_cvt_pk_bf16_f32 v201, v82, v83
	v_cvt_pk_bf16_f32 v202, v84, v85
	v_cvt_pk_bf16_f32 v203, v86, v87
	v_cvt_pk_bf16_f32 v204, v88, v89
	v_cvt_pk_bf16_f32 v205, v90, v91
	v_cvt_pk_bf16_f32 v206, v92, v93
	v_cvt_pk_bf16_f32 v207, v94, v95
	s_nop 0
	v_permlane32_swap_b32_e32 v192, v194
	v_permlane32_swap_b32_e32 v193, v195
	v_permlane32_swap_b32_e32 v196, v198
	v_permlane32_swap_b32_e32 v197, v199
	v_permlane32_swap_b32_e32 v200, v202
	v_permlane32_swap_b32_e32 v201, v203
	v_permlane32_swap_b32_e32 v204, v206
	v_permlane32_swap_b32_e32 v205, v207

.LBB0_1389:
	global_load_dwordx4 v[10:13], v248, s[98:99]
	global_load_dwordx4 v[208:211], v249, s[98:99]
	global_load_dwordx4 v[2:5], v248, s[100:101]
	global_load_dwordx4 v[6:9], v249, s[100:101]
	s_and_b64 vcc, exec, s[4:5]
	s_cbranch_vccnz .LBB0_1388

; template <int MODE>
; __device__ __forceinline__ void attn_block(const BlockRef& cur, const BlockRef& nxt, char* lds, Seam& S, int par, const int wid) {
;     ...
;     for (int t = 1; t + 1 < NT; t += 2) {
;         HALF_STEP(pB0, pB1, mnB, alB, actB, bitB, pA0, pA1, alA, actA, t, 1, 0, 0);
;         HALF_STEP(pA0, pA1, mnA, alA, actA, bitA, pB0, pB1, alB, actB, t + 1, 0, 1, 1);
;     }
.LBB0_1432:
	s_addk_i32 s95, 0x80
	s_add_i32 s4, s96, 2
	s_add_i32 s5, s96, 1
	s_mov_b64 s[6:7], 0x8000
	s_add_u32 s98, s98, 0x4000
	s_addc_u32 s99, s99, 0
	s_add_u32 s100, s100, 0x4000
	s_addc_u32 s101, s101, 0
	v_add_u32_e32 v237, 0xfffffe00, v237
	v_add_u32_e32 v238, 0xffffff80, v238
	s_cmp_gt_u32 s5, s47
	s_waitcnt lgkmcnt(0)
	s_cbranch_scc1 .Lselb_exit
	s_mov_b32 s96, s4
	s_add_i32 s5, s96, -2
	s_and_b32 s4, s5, 31
	s_cmp_lg_u32 s4, 0
	s_cbranch_scc1 .LBB0_1330
	s_branch .LBB0_1329
